# batch all loads of a row in the modnorm pre-pass (hand-written loop) on top of MFMA-interleaved LDS stores
# speedup vs baseline: 1.0251x; 1.0155x over previous
.LBB0_143:
	s_andn2_b64 vcc, exec, s[10:11]
	s_cbranch_vccnz .LBB0_148
	s_mov_b64 s[12:13], s[84:85]
	v_mov_b32 v0, v194
	v_readlane_b32 s2, v247, 18
	s_waitcnt vmcnt(0) lgkmcnt(0)
	v_ashrrev_i32_e32 v2, 6, v0
	v_add_u32_e32 v2, s2, v2
	s_movk_i32 s2, 0x3000
	v_cmp_gt_i32_e32 vcc, s2, v2
	s_and_saveexec_b64 s[10:11], vcc
	v_readlane_b32 s20, v247, 53
	v_readlane_b32 s21, v247, 54
	s_movk_i32 s21, 0x2fff
	s_mov_b32 s23, 0x800000
	s_movk_i32 s24, 0xfff
	v_readlane_b32 s26, v246, 28
	s_cbranch_execz .LBB0_147
	v_readlane_b32 s6, v246, 26
	s_cmp_eq_u32 s6, 3
	s_load_dwordx2 s[16:17], s[12:13], 0x108
	s_load_dwordx2 s[18:19], s[12:13], 0x60
	s_cselect_b32 s2, 1, 2
	s_cmp_lg_u32 s6, 0
	s_cselect_b32 s2, s2, 0
	v_readlane_b32 s6, v246, 27
	s_add_i32 s14, s2, s6
	s_ashr_i32 s15, s14, 31
	s_mul_i32 s9, s14, 0xc0000
	s_mul_hi_i32 s6, s14, 0xc0000
	s_waitcnt lgkmcnt(0)
	s_add_u32 s9, s16, s9
	s_addc_u32 s6, s17, s6
	s_add_u32 s12, s9, 0x7200000
	s_addc_u32 s13, s6, 0
	s_lshl_b64 s[14:15], s[14:15], 12
	s_add_u32 s18, s18, s14
	v_lshlrev_b32_e32 v0, 2, v0
	s_addc_u32 s19, s19, s15
	v_and_b32_e32 v0, 0xfc, v0
	s_add_u32 s14, s16, 0x7bc0000
	v_lshlrev_b32_e32 v6, 2, v0
	v_mov_b32_e32 v7, v1
	v_lshlrev_b32_e32 v8, 1, v0
	v_mov_b32_e32 v9, v1
	s_addc_u32 s15, s17, 0
	v_lshl_add_u64 v[4:5], s[18:19], 0, v[6:7]
	v_or_b32_e32 v10, 0x100, v0
	v_or_b32_e32 v12, 0x200, v0
	v_or_b32_e32 v14, 0x300, v0
	v_lshl_add_u64 v[6:7], s[16:17], 0, v[6:7]
	v_lshl_add_u64 v[8:9], s[16:17], 0, v[8:9]
	s_mov_b64 s[16:17], 0x14958100
	s_mul_i32 s2, s2, 3
	v_lshl_add_u64 v[8:9], v[8:9], 0, s[16:17]
	s_mov_b64 s[16:17], 0
	v_lshlrev_b32_e32 v0, 2, v0
	v_lshlrev_b32_e32 v10, 2, v10
	v_lshlrev_b32_e32 v12, 2, v12
	v_lshlrev_b32_e32 v14, 2, v14
	global_load_dwordx4 v[114:117], v[4:5], off offset:0
	global_load_dwordx4 v[118:121], v[4:5], off offset:1024
	global_load_dwordx4 v[122:125], v[4:5], off offset:2048
	global_load_dwordx4 v[126:129], v[4:5], off offset:3072
.LBB0_146:
	v_ashrrev_i32_e32 v3, 31, v2
	v_lshlrev_b32_e32 v16, 2, v2
	global_load_dword v50, v16, s[12:13]
	v_add_u32_e32 v51, 0xc000, v16
	global_load_dword v51, v51, s[12:13]
	v_add_u32_e32 v52, 0x18000, v16
	global_load_dword v52, v52, s[12:13]
	v_add_u32_e32 v53, 0x24000, v16
	global_load_dword v53, v53, s[12:13]
	v_add_u32_e32 v54, 0x30000, v16
	global_load_dword v54, v54, s[12:13]
	v_add_u32_e32 v55, 0x3c000, v16
	global_load_dword v55, v55, s[12:13]
	v_add_u32_e32 v56, 0x48000, v16
	global_load_dword v56, v56, s[12:13]
	v_add_u32_e32 v57, 0x54000, v16
	global_load_dword v57, v57, s[12:13]
	v_add_u32_e32 v58, 0x60000, v16
	global_load_dword v58, v58, s[12:13]
	v_add_u32_e32 v59, 0x6c000, v16
	global_load_dword v59, v59, s[12:13]
	v_add_u32_e32 v60, 0x78000, v16
	global_load_dword v60, v60, s[12:13]
	v_add_u32_e32 v61, 0x84000, v16
	global_load_dword v61, v61, s[12:13]
	v_add_u32_e32 v62, 0x90000, v16
	global_load_dword v62, v62, s[12:13]
	v_add_u32_e32 v63, 0x9c000, v16
	global_load_dword v63, v63, s[12:13]
	v_add_u32_e32 v64, 0xa8000, v16
	global_load_dword v64, v64, s[12:13]
	v_add_u32_e32 v65, 0xb4000, v16
	global_load_dword v65, v65, s[12:13]
	v_lshlrev_b64 v[36:37], 12, v[2:3]
	v_lshl_add_u64 v[36:37], v[6:7], 0, v[36:37]
	global_load_dwordx4 v[66:69], v[36:37], off offset:0
	global_load_dwordx4 v[70:73], v[36:37], off offset:1024
	global_load_dwordx4 v[74:77], v[36:37], off offset:2048
	global_load_dwordx4 v[78:81], v[36:37], off offset:3072
	v_add_u32_e32 v11, 0xfffff000, v2
	v_lshrrev_b32_e32 v11, 11, v11
	v_add_u32_e32 v11, 1, v11
	v_cmp_lt_i32_e32 vcc, s24, v2
	s_nop 1
	v_cndmask_b32_e32 v11, 0, v11, vcc
	v_add_u32_e32 v11, s26, v11
	v_mad_i64_i32 v[44:45], s[18:19], v11, 9, s[2:3]
	v_lshlrev_b64 v[44:45], 12, v[44:45]
	v_lshl_add_u64 v[28:29], s[14:15], 0, v[44:45]
	v_lshl_add_u64 v[38:39], v[28:29], 0, v[0:1]
	v_add_co_u32_e32 v34, vcc, 0x1000, v38
	s_nop 1
	v_addc_co_u32_e32 v35, vcc, 0, v39, vcc
	global_load_dwordx4 v[82:85], v[34:35], off offset:0
	global_load_dwordx4 v[86:89], v[34:35], off offset:1024
	global_load_dwordx4 v[90:93], v[34:35], off offset:2048
	global_load_dwordx4 v[94:97], v[34:35], off offset:3072
	global_load_dwordx4 v[98:101], v[38:39], off offset:0
	global_load_dwordx4 v[102:105], v[38:39], off offset:1024
	global_load_dwordx4 v[106:109], v[38:39], off offset:2048
	global_load_dwordx4 v[110:113], v[38:39], off offset:3072
	v_lshlrev_b64 v[40:41], 11, v[2:3]
	v_lshl_add_u64 v[40:41], v[8:9], 0, v[40:41]
	v_add_u32_e32 v2, s20, v2
	v_cmp_lt_i32_e32 vcc, s21, v2
	s_or_b64 s[16:17], vcc, s[16:17]
	s_waitcnt vmcnt(27)
	v_add_f32_e32 v11, 0, v50
	s_waitcnt vmcnt(26)
	v_add_f32_e32 v11, v11, v51
	s_waitcnt vmcnt(25)
	v_add_f32_e32 v11, v11, v52
	s_waitcnt vmcnt(24)
	v_add_f32_e32 v11, v11, v53
	s_waitcnt vmcnt(23)
	v_add_f32_e32 v11, v11, v54
	s_waitcnt vmcnt(22)
	v_add_f32_e32 v11, v11, v55
	s_waitcnt vmcnt(21)
	v_add_f32_e32 v11, v11, v56
	s_waitcnt vmcnt(20)
	v_add_f32_e32 v11, v11, v57
	s_waitcnt vmcnt(19)
	v_add_f32_e32 v11, v11, v58
	s_waitcnt vmcnt(18)
	v_add_f32_e32 v11, v11, v59
	s_waitcnt vmcnt(17)
	v_add_f32_e32 v11, v11, v60
	s_waitcnt vmcnt(16)
	v_add_f32_e32 v11, v11, v61
	s_waitcnt vmcnt(15)
	v_add_f32_e32 v11, v11, v62
	s_waitcnt vmcnt(14)
	v_add_f32_e32 v11, v11, v63
	s_waitcnt vmcnt(13)
	v_add_f32_e32 v11, v11, v64
	s_waitcnt vmcnt(12)
	v_add_f32_e32 v11, v11, v65
	v_fmamk_f32 v11, v11, 0x3a800000, v198
	v_mul_f32_e32 v13, 0x4b800000, v11
	v_cmp_gt_f32_e32 vcc, s23, v11
	s_nop 1
	v_cndmask_b32_e32 v11, v11, v13, vcc
	v_rsq_f32_e32 v11, v11
	s_nop 0
	v_mul_f32_e32 v13, 0x45800000, v11
	v_cndmask_b32_e32 v32, v11, v13, vcc
	s_nop 0
	s_waitcnt vmcnt(7)
	v_pk_add_f32 v[82:83], v[82:83], 1.0 op_sel_hi:[1,0]
	v_pk_add_f32 v[84:85], v[84:85], 1.0 op_sel_hi:[1,0]
	v_pk_mul_f32 v[66:67], v[32:33], v[66:67] op_sel_hi:[0,1]
	v_pk_mul_f32 v[68:69], v[32:33], v[68:69] op_sel_hi:[0,1]
	v_pk_mul_f32 v[82:83], v[114:115], v[82:83]
	v_pk_mul_f32 v[84:85], v[116:117], v[84:85]
	s_waitcnt vmcnt(3)
	v_pk_fma_f32 v[66:67], v[66:67], v[82:83], v[98:99]
	v_pk_fma_f32 v[68:69], v[68:69], v[84:85], v[100:101]
	v_cvt_pk_bf16_f32 v66, v66, v67
	v_cvt_pk_bf16_f32 v67, v68, v69
	s_waitcnt vmcnt(6)
	v_pk_add_f32 v[86:87], v[86:87], 1.0 op_sel_hi:[1,0]
	v_pk_add_f32 v[88:89], v[88:89], 1.0 op_sel_hi:[1,0]
	v_pk_mul_f32 v[70:71], v[32:33], v[70:71] op_sel_hi:[0,1]
	v_pk_mul_f32 v[72:73], v[32:33], v[72:73] op_sel_hi:[0,1]
	v_pk_mul_f32 v[86:87], v[118:119], v[86:87]
	v_pk_mul_f32 v[88:89], v[120:121], v[88:89]
	s_waitcnt vmcnt(2)
	v_pk_fma_f32 v[70:71], v[70:71], v[86:87], v[102:103]
	v_pk_fma_f32 v[72:73], v[72:73], v[88:89], v[104:105]
	v_cvt_pk_bf16_f32 v70, v70, v71
	v_cvt_pk_bf16_f32 v71, v72, v73
	s_waitcnt vmcnt(5)
	v_pk_add_f32 v[90:91], v[90:91], 1.0 op_sel_hi:[1,0]
	v_pk_add_f32 v[92:93], v[92:93], 1.0 op_sel_hi:[1,0]
	v_pk_mul_f32 v[74:75], v[32:33], v[74:75] op_sel_hi:[0,1]
	v_pk_mul_f32 v[76:77], v[32:33], v[76:77] op_sel_hi:[0,1]
	v_pk_mul_f32 v[90:91], v[122:123], v[90:91]
	v_pk_mul_f32 v[92:93], v[124:125], v[92:93]
	s_waitcnt vmcnt(1)
	v_pk_fma_f32 v[74:75], v[74:75], v[90:91], v[106:107]
	v_pk_fma_f32 v[76:77], v[76:77], v[92:93], v[108:109]
	v_cvt_pk_bf16_f32 v74, v74, v75
	v_cvt_pk_bf16_f32 v75, v76, v77
	s_waitcnt vmcnt(4)
	v_pk_add_f32 v[94:95], v[94:95], 1.0 op_sel_hi:[1,0]
	v_pk_add_f32 v[96:97], v[96:97], 1.0 op_sel_hi:[1,0]
	v_pk_mul_f32 v[78:79], v[32:33], v[78:79] op_sel_hi:[0,1]
	v_pk_mul_f32 v[80:81], v[32:33], v[80:81] op_sel_hi:[0,1]
	v_pk_mul_f32 v[94:95], v[126:127], v[94:95]
	v_pk_mul_f32 v[96:97], v[128:129], v[96:97]
	s_waitcnt vmcnt(0)
	v_pk_fma_f32 v[78:79], v[78:79], v[94:95], v[110:111]
	v_pk_fma_f32 v[80:81], v[80:81], v[96:97], v[112:113]
	v_cvt_pk_bf16_f32 v78, v78, v79
	v_cvt_pk_bf16_f32 v79, v80, v81
	global_store_dwordx2 v[40:41], v[66:67], off offset:0
	global_store_dwordx2 v[40:41], v[70:71], off offset:512
	global_store_dwordx2 v[40:41], v[74:75], off offset:1024
	global_store_dwordx2 v[40:41], v[78:79], off offset:1536
	s_andn2_b64 exec, exec, s[16:17]
	s_cbranch_execnz .LBB0_146
